# v25 + saddr-form K-loop DMA + permlane-swap reductions + peeled first K-loop pass (combination)
# baseline (speedup 1.0000x reference)
; #define PG8_STAGE(bufoff, gbase, voff) do { _Pragma("unroll") for (int _i = 0; _i < 2; ++_i) \
;         __builtin_amdgcn_global_load_lds((const unsigned*)((const char*)(gbase) + (voff)[_i]), (PG8_LAS unsigned*)(lds + (bufoff) + ldsw + _i * 8192), 16, 0, 0); } while (0)
; #define PG8_LDA(dst, b, h) do { _Pragma("unroll") for (int m = 0; m < 4; ++m) _Pragma("unroll") for (int k = 0; k < 2; ++k) dst[m][k] = *(const PG8_LAS bf16x8*)(lds + PG8_SA(b, h) + aoff + m * 2048 + k * 1024); } while (0)
; #define PG8_LDB(dst, b, h) do { _Pragma("unroll") for (int n = 0; n < 2; ++n) _Pragma("unroll") for (int k = 0; k < 2; ++k) dst[n][k] = *(const PG8_LAS bf16x8*)(lds + PG8_SB(b, h) + boff + n * 2048 + k * 1024); } while (0)
; #define PG8_WAIT_V(n) asm volatile("s_waitcnt vmcnt(" #n ")" ::: "memory")
; #define PG8_WAIT_L(n) asm volatile("s_waitcnt lgkmcnt(" #n ")" ::: "memory")
; #define PG8_BAR __builtin_amdgcn_s_barrier()
; #define PG8_SCHED __builtin_amdgcn_sched_barrier(0)
; template <class Epi, class Sched, bool ALIGN_EPI = false, bool SP2 = false>
; __device__ __forceinline__ void gemm_phase(PG8_LAS unsigned char* lds, const Gemm g, const Sched& S, const Epi& E) {
;     ...
;         const bool has_next = S.next(ui + 1, nxt);
;         const char* nA = has_next ? (const char*)g.A + (size_t)nxt.pm * tstep : cA; const char* nB = has_next ? (const char*)g.Bt + (size_t)nxt.pn * tstep : cB;
;         for (int t = 0; t < nt; t += 2) {
;             if constexpr (Epi::HAS_MID) { if (t == nt / 2) E.mid(acc, cur, wr, wc, fr, fq); }
;             const bool last = (t == nt - 2);
;             const char* a1 = cA + (size_t)(t + 1) * kstep;
;             const char* a2 = last ? nA : cA + (size_t)(t + 2) * kstep; const char* b2 = last ? nB : cB + (size_t)(t + 2) * kstep;
;             const char* a3 = a2 + kstep; const char* b3 = b2 + kstep;
;             if (last && has_next) S.a_ready(nxt);
;             if constexpr (SP2) {
;             PG8_LDB(B0, 0, 0); PG8_LDB(B1, 0, 1); PG8_SCHED; PG8_LDA(At, 0, 0); PG8_STAGE(PG8_SA(1, 1), a1 + hstep, voffA);
;             PG8_WAIT_V(8); PG8_WAIT_L(0); PG8_BAR; PG8_MMA(0, 0, At, B0); PG8_MMA(0, 1, At, B1); PG8_BAR; PG8_SCHED;
;             PG8_LDA(At, 0, 1); PG8_STAGE(PG8_SB(0, 0), b2, voffB); PG8_STAGE(PG8_SB(0, 1), b2 + hstepB, voffB); PG8_STAGE(PG8_SA(0, 0), a2, voffA);
.LBB0_191:
	s_ashr_i32 s13, s12, 31
	s_lshl_b64 s[14:15], s[12:13], 19
	v_readlane_b32 s16, v241, 53
	v_readlane_b32 s17, v241, 54
	s_add_u32 s14, s16, s14
	s_addc_u32 s15, s17, s15
	s_and_b64 s[16:17], s[2:3], exec
	s_cselect_b32 s5, s15, s21
	s_cselect_b32 s13, s14, s20
	s_ashr_i32 s11, s10, 31
	s_lshl_b64 s[16:17], s[10:11], 19
	v_readlane_b32 s24, v241, 36
	v_readlane_b32 s25, v241, 37
	s_add_u32 s16, s24, s16
	s_addc_u32 s17, s25, s17
	s_and_b64 s[24:25], s[2:3], exec
	s_cselect_b32 s11, s17, s23
	s_cselect_b32 s19, s16, s22
	s_add_u32 s20, s20, 0x40080
	s_addc_u32 s21, s21, 0
	s_add_u32 s73, s22, 0x100
	s_addc_u32 s74, s23, 0
	s_mov_b32 s75, -2
	ds_read_b128 v[146:149], v152
	ds_read_b128 v[156:159], v152 offset:1024
	ds_read_b128 v[160:163], v152 offset:2048
	ds_read_b128 v[164:167], v152 offset:3072
	ds_read_b128 v[168:171], v153
	ds_read_b128 v[172:175], v153 offset:1024
	ds_read_b128 v[176:179], v153 offset:2048
	ds_read_b128 v[180:183], v153 offset:3072
	s_add_u32 s22, s20, 0xfffc0080
	s_addc_u32 s23, s21, -1
	s_cmp_eq_u32 s75, 12
	s_cselect_b32 s25, s5, s23
	s_cselect_b32 s24, s13, s22
	s_cselect_b32 s23, s11, s74
	s_cselect_b32 s22, s19, s73
	v_lshl_add_u64 v[216:217], s[20:21], 0, v[138:139]
	s_add_i32 m0, s27, 0xc000
	ds_read_b128 v[184:187], v154
	ds_read_b128 v[188:191], v154 offset:1024
	ds_read_b128 v[192:195], v154 offset:2048
	ds_read_b128 v[196:199], v154 offset:3072
	ds_read_b128 v[200:203], v154 offset:4096
	ds_read_b128 v[204:207], v154 offset:5120
	ds_read_b128 v[208:211], v154 offset:6144
	ds_read_b128 v[212:215], v154 offset:7168
	global_load_lds_dwordx4 v[216:217], off
	v_lshl_add_u64 v[216:217], s[20:21], 0, v[140:141]
	s_add_i32 m0, s27, 0xe000
	s_nop 0
	global_load_lds_dwordx4 v[216:217], off
	s_waitcnt vmcnt(8)
	s_waitcnt lgkmcnt(0)
	s_barrier
	v_mfma_f32_16x16x32_bf16 v[126:129], v[146:149], v[184:187], 0
	v_mfma_f32_16x16x32_bf16 v[122:125], v[160:163], v[184:187], 0
	v_mfma_f32_16x16x32_bf16 v[114:117], v[146:149], v[192:195], 0
	v_mfma_f32_16x16x32_bf16 v[106:109], v[160:163], v[192:195], 0
	v_mfma_f32_16x16x32_bf16 v[98:101], v[146:149], v[200:203], 0
	v_mfma_f32_16x16x32_bf16 v[90:93], v[160:163], v[200:203], 0
	v_mfma_f32_16x16x32_bf16 v[82:85], v[146:149], v[208:211], 0
	v_mfma_f32_16x16x32_bf16 v[74:77], v[160:163], v[208:211], 0
	v_mfma_f32_16x16x32_bf16 v[126:129], v[156:159], v[188:191], v[126:129]
	v_mfma_f32_16x16x32_bf16 v[122:125], v[164:167], v[188:191], v[122:125]
	v_mfma_f32_16x16x32_bf16 v[114:117], v[156:159], v[196:199], v[114:117]
	v_mfma_f32_16x16x32_bf16 v[106:109], v[164:167], v[196:199], v[106:109]
	v_mfma_f32_16x16x32_bf16 v[98:101], v[156:159], v[204:207], v[98:101]
	v_mfma_f32_16x16x32_bf16 v[90:93], v[164:167], v[204:207], v[90:93]
	v_mfma_f32_16x16x32_bf16 v[82:85], v[156:159], v[212:215], v[82:85]
	v_mfma_f32_16x16x32_bf16 v[74:77], v[164:167], v[212:215], v[74:77]
	v_mfma_f32_16x16x32_bf16 v[118:121], v[168:171], v[184:187], 0
	v_mfma_f32_16x16x32_bf16 v[110:113], v[176:179], v[184:187], 0
	v_mfma_f32_16x16x32_bf16 v[102:105], v[168:171], v[192:195], 0
	v_mfma_f32_16x16x32_bf16 v[94:97], v[176:179], v[192:195], 0
	v_mfma_f32_16x16x32_bf16 v[86:89], v[168:171], v[200:203], 0
	v_mfma_f32_16x16x32_bf16 v[78:81], v[176:179], v[200:203], 0
	v_mfma_f32_16x16x32_bf16 v[70:73], v[168:171], v[208:211], 0
	v_mfma_f32_16x16x32_bf16 v[66:69], v[176:179], v[208:211], 0
	v_mfma_f32_16x16x32_bf16 v[118:121], v[172:175], v[188:191], v[118:121]
	v_mfma_f32_16x16x32_bf16 v[110:113], v[180:183], v[188:191], v[110:113]
	v_mfma_f32_16x16x32_bf16 v[102:105], v[172:175], v[196:199], v[102:105]
	v_mfma_f32_16x16x32_bf16 v[94:97], v[180:183], v[196:199], v[94:97]
	v_mfma_f32_16x16x32_bf16 v[86:89], v[172:175], v[204:207], v[86:89]
	v_mfma_f32_16x16x32_bf16 v[78:81], v[180:183], v[204:207], v[78:81]
	v_mfma_f32_16x16x32_bf16 v[70:73], v[172:175], v[212:215], v[70:73]
	v_mfma_f32_16x16x32_bf16 v[66:69], v[180:183], v[212:215], v[66:69]
	s_barrier
	s_add_i32 s76, s69, s26
	v_lshl_add_u64 v[216:217], s[22:23], 0, v[132:133]
	s_mov_b32 m0, s76
	ds_read_b128 v[184:187], v154 offset:16384
	ds_read_b128 v[188:191], v154 offset:17408
	ds_read_b128 v[192:195], v154 offset:18432
	ds_read_b128 v[196:199], v154 offset:19456
	ds_read_b128 v[200:203], v154 offset:20480
	ds_read_b128 v[204:207], v154 offset:21504
	ds_read_b128 v[208:211], v154 offset:22528
	ds_read_b128 v[212:215], v154 offset:23552
	global_load_lds_dwordx4 v132, s[22:23]
	s_add_i32 m0, s76, 0x2000
	s_add_u32 s76, s22, 0x10000
	v_lshl_add_u64 v[218:219], s[22:23], 0, v[136:137]
	s_addc_u32 s77, s23, 0
	s_add_i32 s78, s70, s26
	global_load_lds_dwordx4 v136, s[22:23]
	s_mov_b32 m0, s78
	v_lshl_add_u64 v[222:223], s[24:25], 0, v[134:135]
	global_load_lds_dwordx4 v132, s[76:77]
	s_add_i32 m0, s78, 0x2000
	s_nop 0
	global_load_lds_dwordx4 v136, s[76:77]
	v_lshl_add_u64 v[220:221], s[24:25], 0, v[130:131]
	s_mov_b32 m0, s27
	s_nop 0
	global_load_lds_dwordx4 v130, s[24:25]
	s_mov_b32 m0, s28
	s_nop 0
	global_load_lds_dwordx4 v134, s[24:25]
	s_waitcnt vmcnt(8)
	s_waitcnt lgkmcnt(0)
	s_barrier
; #define PG8_STAGE(bufoff, gbase, voff) do { _Pragma("unroll") for (int _i = 0; _i < 2; ++_i) \
;         __builtin_amdgcn_global_load_lds((const unsigned*)((const char*)(gbase) + (voff)[_i]), (PG8_LAS unsigned*)(lds + (bufoff) + ldsw + _i * 8192), 16, 0, 0); } while (0)
; #define PG8_LDA(dst, b, h) do { _Pragma("unroll") for (int m = 0; m < 4; ++m) _Pragma("unroll") for (int k = 0; k < 2; ++k) dst[m][k] = *(const PG8_LAS bf16x8*)(lds + PG8_SA(b, h) + aoff + m * 2048 + k * 1024); } while (0)
; #define PG8_LDB(dst, b, h) do { _Pragma("unroll") for (int n = 0; n < 2; ++n) _Pragma("unroll") for (int k = 0; k < 2; ++k) dst[n][k] = *(const PG8_LAS bf16x8*)(lds + PG8_SB(b, h) + boff + n * 2048 + k * 1024); } while (0)
; #define PG8_MMA(ai, bj, At, Bt) do { __builtin_amdgcn_s_setprio(1); _Pragma("unroll") for (int m = 0; m < 4; ++m) _Pragma("unroll") for (int n = 0; n < 2; ++n) _Pragma("unroll") for (int k = 0; k < 2; ++k) \
;         acc[ai][bj][m][n] = __builtin_amdgcn_mfma_f32_16x16x32_bf16(Bt[n][k], At[m][k], acc[ai][bj][m][n], 0, 0, 0); __builtin_amdgcn_s_setprio(0); } while (0)
; #define PG8_WAIT_V(n) asm volatile("s_waitcnt vmcnt(" #n ")" ::: "memory")
; #define PG8_WAIT_L(n) asm volatile("s_waitcnt lgkmcnt(" #n ")" ::: "memory")
; #define PG8_BAR __builtin_amdgcn_s_barrier()
; #define PG8_SCHED __builtin_amdgcn_sched_barrier(0)
; template <class Epi, class Sched, bool ALIGN_EPI = false, bool SP2 = false>
; __device__ __forceinline__ void gemm_phase(PG8_LAS unsigned char* lds, const Gemm g, const Sched& S, const Epi& E) {
;     ...
;             PG8_WAIT_V(8); PG8_WAIT_L(0); PG8_BAR; PG8_MMA(1, 0, At, B0); PG8_MMA(1, 1, At, B1); PG8_BAR; PG8_SCHED;
;             PG8_LDB(B0, 1, 0); PG8_LDB(B1, 1, 1); PG8_SCHED; PG8_LDA(At, 1, 0); PG8_STAGE(PG8_SA(0, 1), a2 + hstep, voffA);
;             PG8_WAIT_V(8); PG8_WAIT_L(0); PG8_BAR; PG8_MMA(0, 0, At, B0); PG8_MMA(0, 1, At, B1); PG8_BAR; PG8_SCHED;
	v_mfma_f32_16x16x32_bf16 v[62:65], v[146:149], v[184:187], 0
	v_mfma_f32_16x16x32_bf16 v[58:61], v[160:163], v[184:187], 0
	v_mfma_f32_16x16x32_bf16 v[50:53], v[146:149], v[192:195], 0
	v_mfma_f32_16x16x32_bf16 v[42:45], v[160:163], v[192:195], 0
	v_mfma_f32_16x16x32_bf16 v[34:37], v[146:149], v[200:203], 0
	v_mfma_f32_16x16x32_bf16 v[26:29], v[160:163], v[200:203], 0
	v_mfma_f32_16x16x32_bf16 v[18:21], v[146:149], v[208:211], 0
	v_mfma_f32_16x16x32_bf16 v[10:13], v[160:163], v[208:211], 0
	v_mfma_f32_16x16x32_bf16 v[62:65], v[156:159], v[188:191], v[62:65]
	v_mfma_f32_16x16x32_bf16 v[58:61], v[164:167], v[188:191], v[58:61]
	v_mfma_f32_16x16x32_bf16 v[50:53], v[156:159], v[196:199], v[50:53]
	v_mfma_f32_16x16x32_bf16 v[42:45], v[164:167], v[196:199], v[42:45]
	v_mfma_f32_16x16x32_bf16 v[34:37], v[156:159], v[204:207], v[34:37]
	v_mfma_f32_16x16x32_bf16 v[26:29], v[164:167], v[204:207], v[26:29]
	v_mfma_f32_16x16x32_bf16 v[18:21], v[156:159], v[212:215], v[18:21]
	v_mfma_f32_16x16x32_bf16 v[10:13], v[164:167], v[212:215], v[10:13]
	v_mfma_f32_16x16x32_bf16 v[54:57], v[168:171], v[184:187], 0
	v_mfma_f32_16x16x32_bf16 v[46:49], v[176:179], v[184:187], 0
	v_mfma_f32_16x16x32_bf16 v[38:41], v[168:171], v[192:195], 0
	v_mfma_f32_16x16x32_bf16 v[30:33], v[176:179], v[192:195], 0
	v_mfma_f32_16x16x32_bf16 v[22:25], v[168:171], v[200:203], 0
	v_mfma_f32_16x16x32_bf16 v[14:17], v[176:179], v[200:203], 0
	v_mfma_f32_16x16x32_bf16 v[6:9], v[168:171], v[208:211], 0
	v_mfma_f32_16x16x32_bf16 v[2:5], v[176:179], v[208:211], 0
	v_mfma_f32_16x16x32_bf16 v[54:57], v[172:175], v[188:191], v[54:57]
	v_mfma_f32_16x16x32_bf16 v[46:49], v[180:183], v[188:191], v[46:49]
	v_mfma_f32_16x16x32_bf16 v[38:41], v[172:175], v[196:199], v[38:41]
	v_mfma_f32_16x16x32_bf16 v[30:33], v[180:183], v[196:199], v[30:33]
	v_mfma_f32_16x16x32_bf16 v[22:25], v[172:175], v[204:207], v[22:25]
	v_mfma_f32_16x16x32_bf16 v[14:17], v[180:183], v[204:207], v[14:17]
	v_mfma_f32_16x16x32_bf16 v[6:9], v[172:175], v[212:215], v[6:9]
	v_mfma_f32_16x16x32_bf16 v[2:5], v[180:183], v[212:215], v[2:5]
	s_barrier
	s_add_i32 s76, 0, 0x18000
	v_add_u32_e32 v155, s76, v150
	s_add_i32 s77, 0, 0x1c000
	ds_read_b128 v[146:149], v155
	ds_read_b128 v[156:159], v155 offset:1024
	ds_read_b128 v[160:163], v155 offset:2048
	ds_read_b128 v[164:167], v155 offset:3072
	v_add_u32_e32 v155, s77, v150
	ds_read_b128 v[168:171], v155
	ds_read_b128 v[172:175], v155 offset:1024
	ds_read_b128 v[176:179], v155 offset:2048
	ds_read_b128 v[180:183], v155 offset:3072
	s_add_u32 s24, s24, 0x40000
	s_addc_u32 s25, s25, 0
	s_mov_b32 m0, s29
	ds_read_b128 v[184:187], v154 offset:32768
	ds_read_b128 v[188:191], v154 offset:33792
	ds_read_b128 v[192:195], v154 offset:34816
	ds_read_b128 v[196:199], v154 offset:35840
	ds_read_b128 v[200:203], v154 offset:36864
	ds_read_b128 v[204:207], v154 offset:37888
	ds_read_b128 v[208:211], v154 offset:38912
	ds_read_b128 v[212:215], v154 offset:39936
	global_load_lds_dwordx4 v130, s[24:25]
	s_mov_b32 m0, s30
	s_nop 0
	global_load_lds_dwordx4 v134, s[24:25]
	s_waitcnt vmcnt(8)
	s_waitcnt lgkmcnt(0)
	s_barrier
	v_mfma_f32_16x16x32_bf16 v[126:129], v[146:149], v[184:187], v[126:129]
	v_mfma_f32_16x16x32_bf16 v[122:125], v[160:163], v[184:187], v[122:125]
	v_mfma_f32_16x16x32_bf16 v[114:117], v[146:149], v[192:195], v[114:117]
	v_mfma_f32_16x16x32_bf16 v[106:109], v[160:163], v[192:195], v[106:109]
	v_mfma_f32_16x16x32_bf16 v[98:101], v[146:149], v[200:203], v[98:101]
	v_mfma_f32_16x16x32_bf16 v[90:93], v[160:163], v[200:203], v[90:93]
	v_mfma_f32_16x16x32_bf16 v[82:85], v[146:149], v[208:211], v[82:85]
	v_mfma_f32_16x16x32_bf16 v[74:77], v[160:163], v[208:211], v[74:77]
	v_mfma_f32_16x16x32_bf16 v[126:129], v[156:159], v[188:191], v[126:129]
	v_mfma_f32_16x16x32_bf16 v[122:125], v[164:167], v[188:191], v[122:125]
	v_mfma_f32_16x16x32_bf16 v[114:117], v[156:159], v[196:199], v[114:117]
	v_mfma_f32_16x16x32_bf16 v[106:109], v[164:167], v[196:199], v[106:109]
	v_mfma_f32_16x16x32_bf16 v[98:101], v[156:159], v[204:207], v[98:101]
	v_mfma_f32_16x16x32_bf16 v[90:93], v[164:167], v[204:207], v[90:93]
	v_mfma_f32_16x16x32_bf16 v[82:85], v[156:159], v[212:215], v[82:85]
	v_mfma_f32_16x16x32_bf16 v[74:77], v[164:167], v[212:215], v[74:77]
	v_mfma_f32_16x16x32_bf16 v[118:121], v[168:171], v[184:187], v[118:121]
	v_mfma_f32_16x16x32_bf16 v[110:113], v[176:179], v[184:187], v[110:113]
	v_mfma_f32_16x16x32_bf16 v[102:105], v[168:171], v[192:195], v[102:105]
	v_mfma_f32_16x16x32_bf16 v[94:97], v[176:179], v[192:195], v[94:97]
	v_mfma_f32_16x16x32_bf16 v[86:89], v[168:171], v[200:203], v[86:89]
	v_mfma_f32_16x16x32_bf16 v[78:81], v[176:179], v[200:203], v[78:81]
	v_mfma_f32_16x16x32_bf16 v[70:73], v[168:171], v[208:211], v[70:73]
	v_mfma_f32_16x16x32_bf16 v[66:69], v[176:179], v[208:211], v[66:69]
	v_mfma_f32_16x16x32_bf16 v[118:121], v[172:175], v[188:191], v[118:121]
	v_mfma_f32_16x16x32_bf16 v[110:113], v[180:183], v[188:191], v[110:113]
	v_mfma_f32_16x16x32_bf16 v[102:105], v[172:175], v[196:199], v[102:105]
	v_mfma_f32_16x16x32_bf16 v[94:97], v[180:183], v[196:199], v[94:97]
	v_mfma_f32_16x16x32_bf16 v[86:89], v[172:175], v[204:207], v[86:89]
	v_mfma_f32_16x16x32_bf16 v[78:81], v[180:183], v[204:207], v[78:81]
	v_mfma_f32_16x16x32_bf16 v[70:73], v[172:175], v[212:215], v[70:73]
	v_mfma_f32_16x16x32_bf16 v[66:69], v[180:183], v[212:215], v[66:69]
	s_barrier
; #define PG8_STAGE(bufoff, gbase, voff) do { _Pragma("unroll") for (int _i = 0; _i < 2; ++_i) \
;         __builtin_amdgcn_global_load_lds((const unsigned*)((const char*)(gbase) + (voff)[_i]), (PG8_LAS unsigned*)(lds + (bufoff) + ldsw + _i * 8192), 16, 0, 0); } while (0)
; #define PG8_LDA(dst, b, h) do { _Pragma("unroll") for (int m = 0; m < 4; ++m) _Pragma("unroll") for (int k = 0; k < 2; ++k) dst[m][k] = *(const PG8_LAS bf16x8*)(lds + PG8_SA(b, h) + aoff + m * 2048 + k * 1024); } while (0)
; #define PG8_MMA(ai, bj, At, Bt) do { __builtin_amdgcn_s_setprio(1); _Pragma("unroll") for (int m = 0; m < 4; ++m) _Pragma("unroll") for (int n = 0; n < 2; ++n) _Pragma("unroll") for (int k = 0; k < 2; ++k) \
;         acc[ai][bj][m][n] = __builtin_amdgcn_mfma_f32_16x16x32_bf16(Bt[n][k], At[m][k], acc[ai][bj][m][n], 0, 0, 0); __builtin_amdgcn_s_setprio(0); } while (0)
; #define PG8_WAIT_V(n) asm volatile("s_waitcnt vmcnt(" #n ")" ::: "memory")
; #define PG8_WAIT_L(n) asm volatile("s_waitcnt lgkmcnt(" #n ")" ::: "memory")
; #define PG8_BAR __builtin_amdgcn_s_barrier()
; #define PG8_SCHED __builtin_amdgcn_sched_barrier(0)
; template <class Epi, class Sched, bool ALIGN_EPI = false, bool SP2 = false>
; __device__ __forceinline__ void gemm_phase(PG8_LAS unsigned char* lds, const Gemm g, const Sched& S, const Epi& E) {
;     ...
;             PG8_LDA(At, 1, 1); PG8_STAGE(PG8_SB(1, 0), b3, voffB); PG8_STAGE(PG8_SB(1, 1), b3 + hstepB, voffB); PG8_STAGE(PG8_SA(1, 0), a3, voffA);
;             PG8_WAIT_V(8); PG8_WAIT_L(0); PG8_BAR; PG8_MMA(1, 0, At, B0); PG8_MMA(1, 1, At, B1); PG8_BAR; PG8_SCHED;
	s_add_i32 s24, s76, s26
	v_lshl_add_u64 v[216:217], v[216:217], 0, s[6:7]
	s_mov_b32 m0, s24
	ds_read_b128 v[184:187], v154 offset:49152
	ds_read_b128 v[188:191], v154 offset:50176
	ds_read_b128 v[192:195], v154 offset:51200
	ds_read_b128 v[196:199], v154 offset:52224
	ds_read_b128 v[200:203], v154 offset:53248
	ds_read_b128 v[204:207], v154 offset:54272
	ds_read_b128 v[208:211], v154 offset:55296
	ds_read_b128 v[212:215], v154 offset:56320
	global_load_lds_dwordx4 v[216:217], off
	s_add_i32 m0, s24, 0x2000
	s_add_u32 s22, s22, 0x10080
	v_lshl_add_u64 v[216:217], v[218:219], 0, s[6:7]
	s_addc_u32 s23, s23, 0
	s_add_i32 s24, s77, s26
	global_load_lds_dwordx4 v[216:217], off
	s_mov_b32 m0, s24
	s_nop 0
	global_load_lds_dwordx4 v132, s[22:23]
	s_add_i32 m0, s24, 0x2000
	s_nop 0
	global_load_lds_dwordx4 v136, s[22:23]
	v_lshl_add_u64 v[216:217], v[220:221], 0, s[6:7]
	s_mov_b32 m0, s33
	s_nop 0
	global_load_lds_dwordx4 v[216:217], off
	v_lshl_add_u64 v[216:217], v[222:223], 0, s[6:7]
	s_mov_b32 m0, s34
	s_nop 0
	global_load_lds_dwordx4 v[216:217], off
	s_waitcnt vmcnt(8)
	s_waitcnt lgkmcnt(0)
	s_barrier
	v_mfma_f32_16x16x32_bf16 v[62:65], v[146:149], v[184:187], v[62:65]
	v_mfma_f32_16x16x32_bf16 v[58:61], v[160:163], v[184:187], v[58:61]
	v_mfma_f32_16x16x32_bf16 v[50:53], v[146:149], v[192:195], v[50:53]
	v_mfma_f32_16x16x32_bf16 v[42:45], v[160:163], v[192:195], v[42:45]
	v_mfma_f32_16x16x32_bf16 v[34:37], v[146:149], v[200:203], v[34:37]
	v_mfma_f32_16x16x32_bf16 v[26:29], v[160:163], v[200:203], v[26:29]
	v_mfma_f32_16x16x32_bf16 v[18:21], v[146:149], v[208:211], v[18:21]
	v_mfma_f32_16x16x32_bf16 v[10:13], v[160:163], v[208:211], v[10:13]
	v_mfma_f32_16x16x32_bf16 v[62:65], v[156:159], v[188:191], v[62:65]
	v_mfma_f32_16x16x32_bf16 v[58:61], v[164:167], v[188:191], v[58:61]
	v_mfma_f32_16x16x32_bf16 v[50:53], v[156:159], v[196:199], v[50:53]
	v_mfma_f32_16x16x32_bf16 v[42:45], v[164:167], v[196:199], v[42:45]
	v_mfma_f32_16x16x32_bf16 v[34:37], v[156:159], v[204:207], v[34:37]
	v_mfma_f32_16x16x32_bf16 v[26:29], v[164:167], v[204:207], v[26:29]
	v_mfma_f32_16x16x32_bf16 v[18:21], v[156:159], v[212:215], v[18:21]
	v_mfma_f32_16x16x32_bf16 v[10:13], v[164:167], v[212:215], v[10:13]
	v_mfma_f32_16x16x32_bf16 v[54:57], v[168:171], v[184:187], v[54:57]
	v_mfma_f32_16x16x32_bf16 v[46:49], v[176:179], v[184:187], v[46:49]
	v_mfma_f32_16x16x32_bf16 v[38:41], v[168:171], v[192:195], v[38:41]
	v_mfma_f32_16x16x32_bf16 v[30:33], v[176:179], v[192:195], v[30:33]
	v_mfma_f32_16x16x32_bf16 v[22:25], v[168:171], v[200:203], v[22:25]
	v_mfma_f32_16x16x32_bf16 v[14:17], v[176:179], v[200:203], v[14:17]
	v_mfma_f32_16x16x32_bf16 v[6:9], v[168:171], v[208:211], v[6:9]
	v_mfma_f32_16x16x32_bf16 v[2:5], v[176:179], v[208:211], v[2:5]
	v_mfma_f32_16x16x32_bf16 v[54:57], v[172:175], v[188:191], v[54:57]
	v_mfma_f32_16x16x32_bf16 v[46:49], v[180:183], v[188:191], v[46:49]
	v_mfma_f32_16x16x32_bf16 v[38:41], v[172:175], v[196:199], v[38:41]
	v_mfma_f32_16x16x32_bf16 v[30:33], v[180:183], v[196:199], v[30:33]
	v_mfma_f32_16x16x32_bf16 v[22:25], v[172:175], v[204:207], v[22:25]
	v_mfma_f32_16x16x32_bf16 v[14:17], v[180:183], v[204:207], v[14:17]
	v_mfma_f32_16x16x32_bf16 v[6:9], v[172:175], v[212:215], v[6:9]
	v_mfma_f32_16x16x32_bf16 v[2:5], v[180:183], v[212:215], v[2:5]
	s_barrier
	s_add_i32 s75, s75, 2
	s_add_u32 s20, s20, 0x100
	s_addc_u32 s21, s21, 0
	s_add_u32 s73, s73, 0x100
	s_addc_u32 s74, s74, 0
	s_cmp_gt_u32 s75, 13
	s_cbranch_scc1 .Lpp0_x

; #define PG8_STAGE(bufoff, gbase, voff) do { _Pragma("unroll") for (int _i = 0; _i < 2; ++_i) \
;         __builtin_amdgcn_global_load_lds((const unsigned*)((const char*)(gbase) + (voff)[_i]), (PG8_LAS unsigned*)(lds + (bufoff) + ldsw + _i * 8192), 16, 0, 0); } while (0)
; #define PG8_LDA(dst, b, h) do { _Pragma("unroll") for (int m = 0; m < 4; ++m) _Pragma("unroll") for (int k = 0; k < 2; ++k) dst[m][k] = *(const PG8_LAS bf16x8*)(lds + PG8_SA(b, h) + aoff + m * 2048 + k * 1024); } while (0)
; #define PG8_LDB(dst, b, h) do { _Pragma("unroll") for (int n = 0; n < 2; ++n) _Pragma("unroll") for (int k = 0; k < 2; ++k) dst[n][k] = *(const PG8_LAS bf16x8*)(lds + PG8_SB(b, h) + boff + n * 2048 + k * 1024); } while (0)
; #define PG8_WAIT_V(n) asm volatile("s_waitcnt vmcnt(" #n ")" ::: "memory")
; #define PG8_WAIT_L(n) asm volatile("s_waitcnt lgkmcnt(" #n ")" ::: "memory")
; #define PG8_BAR __builtin_amdgcn_s_barrier()
; #define PG8_SCHED __builtin_amdgcn_sched_barrier(0)
; template <class Epi, class Sched, bool ALIGN_EPI = false, bool SP2 = false>
; __device__ __forceinline__ void gemm_phase(PG8_LAS unsigned char* lds, const Gemm g, const Sched& S, const Epi& E) {
;     ...
;         const bool has_next = S.next(ui + 1, nxt);
;         const char* nA = has_next ? (const char*)g.A + (size_t)nxt.pm * tstep : cA; const char* nB = has_next ? (const char*)g.Bt + (size_t)nxt.pn * tstep : cB;
;         for (int t = 0; t < nt; t += 2) {
;             if constexpr (Epi::HAS_MID) { if (t == nt / 2) E.mid(acc, cur, wr, wc, fr, fq); }
;             const bool last = (t == nt - 2);
;             const char* a1 = cA + (size_t)(t + 1) * kstep;
;             const char* a2 = last ? nA : cA + (size_t)(t + 2) * kstep; const char* b2 = last ? nB : cB + (size_t)(t + 2) * kstep;
;             const char* a3 = a2 + kstep; const char* b3 = b2 + kstep;
;             if (last && has_next) S.a_ready(nxt);
;             if constexpr (SP2) {
;             PG8_LDB(B0, 0, 0); PG8_LDB(B1, 0, 1); PG8_SCHED; PG8_LDA(At, 0, 0); PG8_STAGE(PG8_SA(1, 1), a1 + hstep, voffA);
;             PG8_WAIT_V(8); PG8_WAIT_L(0); PG8_BAR; PG8_MMA(0, 0, At, B0); PG8_MMA(0, 1, At, B1); PG8_BAR; PG8_SCHED;
;             PG8_LDA(At, 0, 1); PG8_STAGE(PG8_SB(0, 0), b2, voffB); PG8_STAGE(PG8_SB(0, 1), b2 + hstepB, voffB); PG8_STAGE(PG8_SA(0, 0), a2, voffA);
.LBB0_1312:
	s_ashr_i32 s27, s26, 31
	s_lshl_b64 s[28:29], s[26:27], 19
	s_add_u32 s28, s12, s28
	s_addc_u32 s29, s13, s29
	s_and_b64 s[34:35], s[6:7], exec
	s_cselect_b32 s9, s29, s39
	s_cselect_b32 s27, s28, s38
	s_ashr_i32 s25, s24, 31
	s_lshl_b64 s[34:35], s[24:25], 19
	s_add_u32 s34, s78, s34
	s_addc_u32 s35, s79, s35
	s_and_b64 s[42:43], s[6:7], exec
	s_cselect_b32 s25, s35, s41
	s_cselect_b32 s37, s34, s40
	s_add_u32 s38, s38, 0x40080
	s_addc_u32 s39, s39, 0
	s_add_u32 s59, s40, 0x100
	s_addc_u32 s60, s41, 0
	s_mov_b32 s61, -2
	ds_read_b128 v[146:149], v154
	ds_read_b128 v[158:161], v154 offset:1024
	ds_read_b128 v[162:165], v154 offset:2048
	ds_read_b128 v[166:169], v154 offset:3072
	ds_read_b128 v[170:173], v155
	ds_read_b128 v[174:177], v155 offset:1024
	ds_read_b128 v[178:181], v155 offset:2048
	ds_read_b128 v[182:185], v155 offset:3072
	s_add_u32 s40, s38, 0xfffc0080
	s_addc_u32 s41, s39, -1
	s_cmp_eq_u32 s61, 12
	s_cselect_b32 s43, s9, s41
	s_cselect_b32 s42, s27, s40
	s_cselect_b32 s41, s25, s60
	s_cselect_b32 s40, s37, s59
	v_lshl_add_u64 v[150:151], s[38:39], 0, v[138:139]
	s_add_i32 m0, s31, 0xc000
	ds_read_b128 v[186:189], v156
	ds_read_b128 v[190:193], v156 offset:1024
	ds_read_b128 v[194:197], v156 offset:2048
	ds_read_b128 v[198:201], v156 offset:3072
	ds_read_b128 v[202:205], v156 offset:4096
	ds_read_b128 v[206:209], v156 offset:5120
	ds_read_b128 v[210:213], v156 offset:6144
	ds_read_b128 v[214:217], v156 offset:7168
	global_load_lds_dwordx4 v[150:151], off
	v_lshl_add_u64 v[150:151], s[38:39], 0, v[140:141]
	s_add_i32 m0, s31, 0xe000
	s_nop 0
	global_load_lds_dwordx4 v[150:151], off
	s_waitcnt vmcnt(8)
	s_waitcnt lgkmcnt(0)
	s_barrier
	v_mfma_f32_16x16x32_bf16 v[126:129], v[146:149], v[186:189], 0
	v_mfma_f32_16x16x32_bf16 v[122:125], v[162:165], v[186:189], 0
	v_mfma_f32_16x16x32_bf16 v[110:113], v[146:149], v[194:197], 0
	v_mfma_f32_16x16x32_bf16 v[106:109], v[162:165], v[194:197], 0
	v_mfma_f32_16x16x32_bf16 v[94:97], v[146:149], v[202:205], 0
	v_mfma_f32_16x16x32_bf16 v[90:93], v[162:165], v[202:205], 0
	v_mfma_f32_16x16x32_bf16 v[78:81], v[146:149], v[210:213], 0
	v_mfma_f32_16x16x32_bf16 v[74:77], v[162:165], v[210:213], 0
	v_mfma_f32_16x16x32_bf16 v[126:129], v[158:161], v[190:193], v[126:129]
	v_mfma_f32_16x16x32_bf16 v[122:125], v[166:169], v[190:193], v[122:125]
	v_mfma_f32_16x16x32_bf16 v[110:113], v[158:161], v[198:201], v[110:113]
	v_mfma_f32_16x16x32_bf16 v[106:109], v[166:169], v[198:201], v[106:109]
	v_mfma_f32_16x16x32_bf16 v[94:97], v[158:161], v[206:209], v[94:97]
	v_mfma_f32_16x16x32_bf16 v[90:93], v[166:169], v[206:209], v[90:93]
	v_mfma_f32_16x16x32_bf16 v[78:81], v[158:161], v[214:217], v[78:81]
	v_mfma_f32_16x16x32_bf16 v[74:77], v[166:169], v[214:217], v[74:77]
	v_mfma_f32_16x16x32_bf16 v[118:121], v[170:173], v[186:189], 0
	v_mfma_f32_16x16x32_bf16 v[114:117], v[178:181], v[186:189], 0
	v_mfma_f32_16x16x32_bf16 v[102:105], v[170:173], v[194:197], 0
	v_mfma_f32_16x16x32_bf16 v[98:101], v[178:181], v[194:197], 0
	v_mfma_f32_16x16x32_bf16 v[86:89], v[170:173], v[202:205], 0
	v_mfma_f32_16x16x32_bf16 v[82:85], v[178:181], v[202:205], 0
	v_mfma_f32_16x16x32_bf16 v[70:73], v[170:173], v[210:213], 0
	v_mfma_f32_16x16x32_bf16 v[66:69], v[178:181], v[210:213], 0
	v_mfma_f32_16x16x32_bf16 v[118:121], v[174:177], v[190:193], v[118:121]
	v_mfma_f32_16x16x32_bf16 v[114:117], v[182:185], v[190:193], v[114:117]
	v_mfma_f32_16x16x32_bf16 v[102:105], v[174:177], v[198:201], v[102:105]
	v_mfma_f32_16x16x32_bf16 v[98:101], v[182:185], v[198:201], v[98:101]
	v_mfma_f32_16x16x32_bf16 v[86:89], v[174:177], v[206:209], v[86:89]
	v_mfma_f32_16x16x32_bf16 v[82:85], v[182:185], v[206:209], v[82:85]
	v_mfma_f32_16x16x32_bf16 v[70:73], v[174:177], v[214:217], v[70:73]
	v_mfma_f32_16x16x32_bf16 v[66:69], v[182:185], v[214:217], v[66:69]
	s_barrier
	s_add_i32 s62, s57, s30
	v_lshl_add_u64 v[150:151], s[40:41], 0, v[132:133]
	s_mov_b32 m0, s62
	ds_read_b128 v[186:189], v156 offset:16384
	ds_read_b128 v[190:193], v156 offset:17408
	ds_read_b128 v[194:197], v156 offset:18432
	ds_read_b128 v[198:201], v156 offset:19456
	ds_read_b128 v[202:205], v156 offset:20480
	ds_read_b128 v[206:209], v156 offset:21504
	ds_read_b128 v[210:213], v156 offset:22528
	ds_read_b128 v[214:217], v156 offset:23552
	global_load_lds_dwordx4 v132, s[40:41]
	s_add_i32 m0, s62, 0x2000
	s_add_u32 s62, s40, 0x10000
	v_lshl_add_u64 v[218:219], s[40:41], 0, v[136:137]
	s_addc_u32 s63, s41, 0
	s_add_i32 s64, s58, s30
	global_load_lds_dwordx4 v136, s[40:41]
	s_mov_b32 m0, s64
	v_lshl_add_u64 v[222:223], s[42:43], 0, v[134:135]
	global_load_lds_dwordx4 v132, s[62:63]
	s_add_i32 m0, s64, 0x2000
	s_nop 0
	global_load_lds_dwordx4 v136, s[62:63]
	v_lshl_add_u64 v[220:221], s[42:43], 0, v[130:131]
	s_mov_b32 m0, s31
	s_nop 0
	global_load_lds_dwordx4 v130, s[42:43]
	s_mov_b32 m0, s33
	s_nop 0
	global_load_lds_dwordx4 v134, s[42:43]
	s_waitcnt vmcnt(8)
	s_waitcnt lgkmcnt(0)
	s_barrier
; #define PG8_STAGE(bufoff, gbase, voff) do { _Pragma("unroll") for (int _i = 0; _i < 2; ++_i) \
;         __builtin_amdgcn_global_load_lds((const unsigned*)((const char*)(gbase) + (voff)[_i]), (PG8_LAS unsigned*)(lds + (bufoff) + ldsw + _i * 8192), 16, 0, 0); } while (0)
; #define PG8_LDA(dst, b, h) do { _Pragma("unroll") for (int m = 0; m < 4; ++m) _Pragma("unroll") for (int k = 0; k < 2; ++k) dst[m][k] = *(const PG8_LAS bf16x8*)(lds + PG8_SA(b, h) + aoff + m * 2048 + k * 1024); } while (0)
; #define PG8_LDB(dst, b, h) do { _Pragma("unroll") for (int n = 0; n < 2; ++n) _Pragma("unroll") for (int k = 0; k < 2; ++k) dst[n][k] = *(const PG8_LAS bf16x8*)(lds + PG8_SB(b, h) + boff + n * 2048 + k * 1024); } while (0)
; #define PG8_MMA(ai, bj, At, Bt) do { __builtin_amdgcn_s_setprio(1); _Pragma("unroll") for (int m = 0; m < 4; ++m) _Pragma("unroll") for (int n = 0; n < 2; ++n) _Pragma("unroll") for (int k = 0; k < 2; ++k) \
;         acc[ai][bj][m][n] = __builtin_amdgcn_mfma_f32_16x16x32_bf16(Bt[n][k], At[m][k], acc[ai][bj][m][n], 0, 0, 0); __builtin_amdgcn_s_setprio(0); } while (0)
; #define PG8_WAIT_V(n) asm volatile("s_waitcnt vmcnt(" #n ")" ::: "memory")
; #define PG8_WAIT_L(n) asm volatile("s_waitcnt lgkmcnt(" #n ")" ::: "memory")
; #define PG8_BAR __builtin_amdgcn_s_barrier()
; #define PG8_SCHED __builtin_amdgcn_sched_barrier(0)
; template <class Epi, class Sched, bool ALIGN_EPI = false, bool SP2 = false>
; __device__ __forceinline__ void gemm_phase(PG8_LAS unsigned char* lds, const Gemm g, const Sched& S, const Epi& E) {
;     ...
;             PG8_WAIT_V(8); PG8_WAIT_L(0); PG8_BAR; PG8_MMA(1, 0, At, B0); PG8_MMA(1, 1, At, B1); PG8_BAR; PG8_SCHED;
;             PG8_LDB(B0, 1, 0); PG8_LDB(B1, 1, 1); PG8_SCHED; PG8_LDA(At, 1, 0); PG8_STAGE(PG8_SA(0, 1), a2 + hstep, voffA);
;             PG8_WAIT_V(8); PG8_WAIT_L(0); PG8_BAR; PG8_MMA(0, 0, At, B0); PG8_MMA(0, 1, At, B1); PG8_BAR; PG8_SCHED;
	v_mfma_f32_16x16x32_bf16 v[62:65], v[146:149], v[186:189], 0
	v_mfma_f32_16x16x32_bf16 v[58:61], v[162:165], v[186:189], 0
	v_mfma_f32_16x16x32_bf16 v[46:49], v[146:149], v[194:197], 0
	v_mfma_f32_16x16x32_bf16 v[42:45], v[162:165], v[194:197], 0
	v_mfma_f32_16x16x32_bf16 v[30:33], v[146:149], v[202:205], 0
	v_mfma_f32_16x16x32_bf16 v[26:29], v[162:165], v[202:205], 0
	v_mfma_f32_16x16x32_bf16 v[14:17], v[146:149], v[210:213], 0
	v_mfma_f32_16x16x32_bf16 v[10:13], v[162:165], v[210:213], 0
	v_mfma_f32_16x16x32_bf16 v[62:65], v[158:161], v[190:193], v[62:65]
	v_mfma_f32_16x16x32_bf16 v[58:61], v[166:169], v[190:193], v[58:61]
	v_mfma_f32_16x16x32_bf16 v[46:49], v[158:161], v[198:201], v[46:49]
	v_mfma_f32_16x16x32_bf16 v[42:45], v[166:169], v[198:201], v[42:45]
	v_mfma_f32_16x16x32_bf16 v[30:33], v[158:161], v[206:209], v[30:33]
	v_mfma_f32_16x16x32_bf16 v[26:29], v[166:169], v[206:209], v[26:29]
	v_mfma_f32_16x16x32_bf16 v[14:17], v[158:161], v[214:217], v[14:17]
	v_mfma_f32_16x16x32_bf16 v[10:13], v[166:169], v[214:217], v[10:13]
	v_mfma_f32_16x16x32_bf16 v[54:57], v[170:173], v[186:189], 0
	v_mfma_f32_16x16x32_bf16 v[50:53], v[178:181], v[186:189], 0
	v_mfma_f32_16x16x32_bf16 v[38:41], v[170:173], v[194:197], 0
	v_mfma_f32_16x16x32_bf16 v[34:37], v[178:181], v[194:197], 0
	v_mfma_f32_16x16x32_bf16 v[22:25], v[170:173], v[202:205], 0
	v_mfma_f32_16x16x32_bf16 v[18:21], v[178:181], v[202:205], 0
	v_mfma_f32_16x16x32_bf16 v[6:9], v[170:173], v[210:213], 0
	v_mfma_f32_16x16x32_bf16 v[2:5], v[178:181], v[210:213], 0
	v_mfma_f32_16x16x32_bf16 v[54:57], v[174:177], v[190:193], v[54:57]
	v_mfma_f32_16x16x32_bf16 v[50:53], v[182:185], v[190:193], v[50:53]
	v_mfma_f32_16x16x32_bf16 v[38:41], v[174:177], v[198:201], v[38:41]
	v_mfma_f32_16x16x32_bf16 v[34:37], v[182:185], v[198:201], v[34:37]
	v_mfma_f32_16x16x32_bf16 v[22:25], v[174:177], v[206:209], v[22:25]
	v_mfma_f32_16x16x32_bf16 v[18:21], v[182:185], v[206:209], v[18:21]
	v_mfma_f32_16x16x32_bf16 v[6:9], v[174:177], v[214:217], v[6:9]
	v_mfma_f32_16x16x32_bf16 v[2:5], v[182:185], v[214:217], v[2:5]
	s_barrier
	s_add_i32 s62, 0, 0x18000
	v_add_u32_e32 v157, s62, v152
	s_add_i32 s63, 0, 0x1c000
	ds_read_b128 v[146:149], v157
	ds_read_b128 v[158:161], v157 offset:1024
	ds_read_b128 v[162:165], v157 offset:2048
	ds_read_b128 v[166:169], v157 offset:3072
	v_add_u32_e32 v157, s63, v152
	ds_read_b128 v[170:173], v157
	ds_read_b128 v[174:177], v157 offset:1024
	ds_read_b128 v[178:181], v157 offset:2048
	ds_read_b128 v[182:185], v157 offset:3072
	s_add_u32 s42, s42, 0x40000
	s_addc_u32 s43, s43, 0
	s_mov_b32 m0, s44
	ds_read_b128 v[186:189], v156 offset:32768
	ds_read_b128 v[190:193], v156 offset:33792
	ds_read_b128 v[194:197], v156 offset:34816
	ds_read_b128 v[198:201], v156 offset:35840
	ds_read_b128 v[202:205], v156 offset:36864
	ds_read_b128 v[206:209], v156 offset:37888
	ds_read_b128 v[210:213], v156 offset:38912
	ds_read_b128 v[214:217], v156 offset:39936
	global_load_lds_dwordx4 v130, s[42:43]
	s_mov_b32 m0, s45
	s_nop 0
	global_load_lds_dwordx4 v134, s[42:43]
	s_waitcnt vmcnt(8)
	s_waitcnt lgkmcnt(0)
	s_barrier
	v_mfma_f32_16x16x32_bf16 v[126:129], v[146:149], v[186:189], v[126:129]
	v_mfma_f32_16x16x32_bf16 v[122:125], v[162:165], v[186:189], v[122:125]
	v_mfma_f32_16x16x32_bf16 v[110:113], v[146:149], v[194:197], v[110:113]
	v_mfma_f32_16x16x32_bf16 v[106:109], v[162:165], v[194:197], v[106:109]
	v_mfma_f32_16x16x32_bf16 v[94:97], v[146:149], v[202:205], v[94:97]
	v_mfma_f32_16x16x32_bf16 v[90:93], v[162:165], v[202:205], v[90:93]
	v_mfma_f32_16x16x32_bf16 v[78:81], v[146:149], v[210:213], v[78:81]
	v_mfma_f32_16x16x32_bf16 v[74:77], v[162:165], v[210:213], v[74:77]
	v_mfma_f32_16x16x32_bf16 v[126:129], v[158:161], v[190:193], v[126:129]
	v_mfma_f32_16x16x32_bf16 v[122:125], v[166:169], v[190:193], v[122:125]
	v_mfma_f32_16x16x32_bf16 v[110:113], v[158:161], v[198:201], v[110:113]
	v_mfma_f32_16x16x32_bf16 v[106:109], v[166:169], v[198:201], v[106:109]
	v_mfma_f32_16x16x32_bf16 v[94:97], v[158:161], v[206:209], v[94:97]
	v_mfma_f32_16x16x32_bf16 v[90:93], v[166:169], v[206:209], v[90:93]
	v_mfma_f32_16x16x32_bf16 v[78:81], v[158:161], v[214:217], v[78:81]
	v_mfma_f32_16x16x32_bf16 v[74:77], v[166:169], v[214:217], v[74:77]
	v_mfma_f32_16x16x32_bf16 v[118:121], v[170:173], v[186:189], v[118:121]
	v_mfma_f32_16x16x32_bf16 v[114:117], v[178:181], v[186:189], v[114:117]
	v_mfma_f32_16x16x32_bf16 v[102:105], v[170:173], v[194:197], v[102:105]
	v_mfma_f32_16x16x32_bf16 v[98:101], v[178:181], v[194:197], v[98:101]
	v_mfma_f32_16x16x32_bf16 v[86:89], v[170:173], v[202:205], v[86:89]
	v_mfma_f32_16x16x32_bf16 v[82:85], v[178:181], v[202:205], v[82:85]
	v_mfma_f32_16x16x32_bf16 v[70:73], v[170:173], v[210:213], v[70:73]
	v_mfma_f32_16x16x32_bf16 v[66:69], v[178:181], v[210:213], v[66:69]
	v_mfma_f32_16x16x32_bf16 v[118:121], v[174:177], v[190:193], v[118:121]
	v_mfma_f32_16x16x32_bf16 v[114:117], v[182:185], v[190:193], v[114:117]
	v_mfma_f32_16x16x32_bf16 v[102:105], v[174:177], v[198:201], v[102:105]
	v_mfma_f32_16x16x32_bf16 v[98:101], v[182:185], v[198:201], v[98:101]
	v_mfma_f32_16x16x32_bf16 v[86:89], v[174:177], v[206:209], v[86:89]
	v_mfma_f32_16x16x32_bf16 v[82:85], v[182:185], v[206:209], v[82:85]
	v_mfma_f32_16x16x32_bf16 v[70:73], v[174:177], v[214:217], v[70:73]
	v_mfma_f32_16x16x32_bf16 v[66:69], v[182:185], v[214:217], v[66:69]
	s_barrier
; #define PG8_STAGE(bufoff, gbase, voff) do { _Pragma("unroll") for (int _i = 0; _i < 2; ++_i) \
;         __builtin_amdgcn_global_load_lds((const unsigned*)((const char*)(gbase) + (voff)[_i]), (PG8_LAS unsigned*)(lds + (bufoff) + ldsw + _i * 8192), 16, 0, 0); } while (0)
; #define PG8_LDA(dst, b, h) do { _Pragma("unroll") for (int m = 0; m < 4; ++m) _Pragma("unroll") for (int k = 0; k < 2; ++k) dst[m][k] = *(const PG8_LAS bf16x8*)(lds + PG8_SA(b, h) + aoff + m * 2048 + k * 1024); } while (0)
; #define PG8_MMA(ai, bj, At, Bt) do { __builtin_amdgcn_s_setprio(1); _Pragma("unroll") for (int m = 0; m < 4; ++m) _Pragma("unroll") for (int n = 0; n < 2; ++n) _Pragma("unroll") for (int k = 0; k < 2; ++k) \
;         acc[ai][bj][m][n] = __builtin_amdgcn_mfma_f32_16x16x32_bf16(Bt[n][k], At[m][k], acc[ai][bj][m][n], 0, 0, 0); __builtin_amdgcn_s_setprio(0); } while (0)
; #define PG8_WAIT_V(n) asm volatile("s_waitcnt vmcnt(" #n ")" ::: "memory")
; #define PG8_WAIT_L(n) asm volatile("s_waitcnt lgkmcnt(" #n ")" ::: "memory")
; #define PG8_BAR __builtin_amdgcn_s_barrier()
; #define PG8_SCHED __builtin_amdgcn_sched_barrier(0)
; template <class Epi, class Sched, bool ALIGN_EPI = false, bool SP2 = false>
; __device__ __forceinline__ void gemm_phase(PG8_LAS unsigned char* lds, const Gemm g, const Sched& S, const Epi& E) {
;     ...
;             PG8_LDA(At, 1, 1); PG8_STAGE(PG8_SB(1, 0), b3, voffB); PG8_STAGE(PG8_SB(1, 1), b3 + hstepB, voffB); PG8_STAGE(PG8_SA(1, 0), a3, voffA);
;             PG8_WAIT_V(8); PG8_WAIT_L(0); PG8_BAR; PG8_MMA(1, 0, At, B0); PG8_MMA(1, 1, At, B1); PG8_BAR; PG8_SCHED;
	s_add_i32 s42, s62, s30
	v_lshl_add_u64 v[150:151], v[150:151], 0, s[10:11]
	s_mov_b32 m0, s42
	ds_read_b128 v[186:189], v156 offset:49152
	ds_read_b128 v[190:193], v156 offset:50176
	ds_read_b128 v[194:197], v156 offset:51200
	ds_read_b128 v[198:201], v156 offset:52224
	ds_read_b128 v[202:205], v156 offset:53248
	ds_read_b128 v[206:209], v156 offset:54272
	ds_read_b128 v[210:213], v156 offset:55296
	ds_read_b128 v[214:217], v156 offset:56320
	global_load_lds_dwordx4 v[150:151], off
	s_add_i32 m0, s42, 0x2000
	s_add_u32 s40, s40, 0x10080
	v_lshl_add_u64 v[150:151], v[218:219], 0, s[10:11]
	s_addc_u32 s41, s41, 0
	s_add_i32 s42, s63, s30
	global_load_lds_dwordx4 v[150:151], off
	s_mov_b32 m0, s42
	s_nop 0
	global_load_lds_dwordx4 v132, s[40:41]
	s_add_i32 m0, s42, 0x2000
	s_nop 0
	global_load_lds_dwordx4 v136, s[40:41]
	v_lshl_add_u64 v[150:151], v[220:221], 0, s[10:11]
	s_mov_b32 m0, s47
	s_nop 0
	global_load_lds_dwordx4 v[150:151], off
	v_lshl_add_u64 v[150:151], v[222:223], 0, s[10:11]
	s_mov_b32 m0, s54
	s_nop 0
	global_load_lds_dwordx4 v[150:151], off
	s_waitcnt vmcnt(8)
	s_waitcnt lgkmcnt(0)
	s_barrier
	v_mfma_f32_16x16x32_bf16 v[62:65], v[146:149], v[186:189], v[62:65]
	v_mfma_f32_16x16x32_bf16 v[58:61], v[162:165], v[186:189], v[58:61]
	v_mfma_f32_16x16x32_bf16 v[46:49], v[146:149], v[194:197], v[46:49]
	v_mfma_f32_16x16x32_bf16 v[42:45], v[162:165], v[194:197], v[42:45]
	v_mfma_f32_16x16x32_bf16 v[30:33], v[146:149], v[202:205], v[30:33]
	v_mfma_f32_16x16x32_bf16 v[26:29], v[162:165], v[202:205], v[26:29]
	v_mfma_f32_16x16x32_bf16 v[14:17], v[146:149], v[210:213], v[14:17]
	v_mfma_f32_16x16x32_bf16 v[10:13], v[162:165], v[210:213], v[10:13]
	v_mfma_f32_16x16x32_bf16 v[62:65], v[158:161], v[190:193], v[62:65]
	v_mfma_f32_16x16x32_bf16 v[58:61], v[166:169], v[190:193], v[58:61]
	v_mfma_f32_16x16x32_bf16 v[46:49], v[158:161], v[198:201], v[46:49]
	v_mfma_f32_16x16x32_bf16 v[42:45], v[166:169], v[198:201], v[42:45]
	v_mfma_f32_16x16x32_bf16 v[30:33], v[158:161], v[206:209], v[30:33]
	v_mfma_f32_16x16x32_bf16 v[26:29], v[166:169], v[206:209], v[26:29]
	v_mfma_f32_16x16x32_bf16 v[14:17], v[158:161], v[214:217], v[14:17]
	v_mfma_f32_16x16x32_bf16 v[10:13], v[166:169], v[214:217], v[10:13]
	v_mfma_f32_16x16x32_bf16 v[54:57], v[170:173], v[186:189], v[54:57]
	v_mfma_f32_16x16x32_bf16 v[50:53], v[178:181], v[186:189], v[50:53]
	v_mfma_f32_16x16x32_bf16 v[38:41], v[170:173], v[194:197], v[38:41]
	v_mfma_f32_16x16x32_bf16 v[34:37], v[178:181], v[194:197], v[34:37]
	v_mfma_f32_16x16x32_bf16 v[22:25], v[170:173], v[202:205], v[22:25]
	v_mfma_f32_16x16x32_bf16 v[18:21], v[178:181], v[202:205], v[18:21]
	v_mfma_f32_16x16x32_bf16 v[6:9], v[170:173], v[210:213], v[6:9]
	v_mfma_f32_16x16x32_bf16 v[2:5], v[178:181], v[210:213], v[2:5]
	v_mfma_f32_16x16x32_bf16 v[54:57], v[174:177], v[190:193], v[54:57]
	v_mfma_f32_16x16x32_bf16 v[50:53], v[182:185], v[190:193], v[50:53]
	v_mfma_f32_16x16x32_bf16 v[38:41], v[174:177], v[198:201], v[38:41]
	v_mfma_f32_16x16x32_bf16 v[34:37], v[182:185], v[198:201], v[34:37]
	v_mfma_f32_16x16x32_bf16 v[22:25], v[174:177], v[206:209], v[22:25]
	v_mfma_f32_16x16x32_bf16 v[18:21], v[182:185], v[206:209], v[18:21]
	v_mfma_f32_16x16x32_bf16 v[6:9], v[174:177], v[214:217], v[6:9]
	v_mfma_f32_16x16x32_bf16 v[2:5], v[182:185], v[214:217], v[2:5]
	s_barrier
	s_add_i32 s61, s61, 2
	s_add_u32 s38, s38, 0x100
	s_addc_u32 s39, s39, 0
	s_add_u32 s59, s59, 0x100
	s_addc_u32 s60, s60, 0
	s_cmp_gt_u32 s61, 13
	s_cbranch_scc1 .Lpp1_x
